# attention QK^T: 3-deep K / 2-deep Q fragment rings with counted lgkmcnt (was read->wait->mfma)
# baseline (speedup 1.0000x reference)
.LBB0_734:
	ds_read_b128 v[194:197], v139 offset:32768
	ds_read_b128 v[226:229], v139 offset:45056
	ds_read_b128 v[234:237], v202 offset:32768
	ds_read_b128 v[230:233], v220
	ds_read_b128 v[238:241], v220 offset:1024
	s_add_i32 s0, s84, 63
	s_cmp_le_i32 s0, s82
	s_waitcnt lgkmcnt(4)
	v_mfma_f32_32x32x16_bf16 v[82:97], v[194:197], v[98:101], 0
	ds_read_b128 v[194:197], v202 offset:45056
	s_waitcnt lgkmcnt(4)
	v_mfma_f32_32x32x16_bf16 v[66:81], v[226:229], v[98:101], 0
	ds_read_b128 v[226:229], v203 offset:32768
	s_waitcnt lgkmcnt(4)
	v_mfma_f32_32x32x16_bf16 v[82:97], v[234:237], v[102:105], v[82:97]
	ds_read_b128 v[234:237], v203 offset:45056
	s_waitcnt lgkmcnt(2)
	v_mfma_f32_32x32x16_bf16 v[66:81], v[194:197], v[102:105], v[66:81]
	ds_read_b128 v[194:197], v204 offset:32768
	s_waitcnt lgkmcnt(2)
	v_mfma_f32_32x32x16_bf16 v[82:97], v[226:229], v[106:109], v[82:97]
	ds_read_b128 v[226:229], v204 offset:45056
	s_waitcnt lgkmcnt(2)
	v_mfma_f32_32x32x16_bf16 v[66:81], v[234:237], v[106:109], v[66:81]
	ds_read_b128 v[234:237], v139 offset:32896
	s_waitcnt lgkmcnt(2)
	v_mfma_f32_32x32x16_bf16 v[82:97], v[194:197], v[110:113], v[82:97]
	ds_read_b128 v[194:197], v139 offset:45184
	s_waitcnt lgkmcnt(2)
	v_mfma_f32_32x32x16_bf16 v[66:81], v[226:229], v[110:113], v[66:81]
	ds_read_b128 v[226:229], v202 offset:32896
	s_waitcnt lgkmcnt(2)
	v_mfma_f32_32x32x16_bf16 v[82:97], v[234:237], v[230:233], v[82:97]
	ds_read_b128 v[234:237], v202 offset:45184
	s_waitcnt lgkmcnt(2)
	v_mfma_f32_32x32x16_bf16 v[66:81], v[194:197], v[230:233], v[66:81]
	ds_read_b128 v[194:197], v203 offset:32896
	ds_read_b128 v[230:233], v220 offset:2048
	s_waitcnt lgkmcnt(3)
	v_mfma_f32_32x32x16_bf16 v[82:97], v[226:229], v[238:241], v[82:97]
	ds_read_b128 v[226:229], v203 offset:45184
	s_waitcnt lgkmcnt(3)
	v_mfma_f32_32x32x16_bf16 v[66:81], v[234:237], v[238:241], v[66:81]
	ds_read_b128 v[234:237], v204 offset:32896
	ds_read_b128 v[238:241], v220 offset:3072
	s_waitcnt lgkmcnt(3)
	v_mfma_f32_32x32x16_bf16 v[82:97], v[194:197], v[230:233], v[82:97]
	ds_read_b128 v[194:197], v204 offset:45184
	s_waitcnt lgkmcnt(3)
	v_mfma_f32_32x32x16_bf16 v[66:81], v[226:229], v[230:233], v[66:81]
	ds_read_b128 v[226:229], v139 offset:33024
	ds_read_b128 v[230:233], v220 offset:4096
	s_waitcnt lgkmcnt(3)
	v_mfma_f32_32x32x16_bf16 v[82:97], v[234:237], v[238:241], v[82:97]
	ds_read_b128 v[234:237], v139 offset:45312
	s_waitcnt lgkmcnt(3)
	v_mfma_f32_32x32x16_bf16 v[66:81], v[194:197], v[238:241], v[66:81]
	ds_read_b128 v[194:197], v202 offset:33024
	ds_read_b128 v[238:241], v220 offset:5120
	s_waitcnt lgkmcnt(3)
	v_mfma_f32_32x32x16_bf16 v[82:97], v[226:229], v[230:233], v[82:97]
	ds_read_b128 v[226:229], v202 offset:45312
	s_waitcnt lgkmcnt(3)
	v_mfma_f32_32x32x16_bf16 v[66:81], v[234:237], v[230:233], v[66:81]
	ds_read_b128 v[234:237], v203 offset:33024
	ds_read_b128 v[230:233], v220 offset:6144
	s_waitcnt lgkmcnt(3)
	v_mfma_f32_32x32x16_bf16 v[82:97], v[194:197], v[238:241], v[82:97]
	ds_read_b128 v[194:197], v203 offset:45312
	s_waitcnt lgkmcnt(3)
	v_mfma_f32_32x32x16_bf16 v[66:81], v[226:229], v[238:241], v[66:81]
	ds_read_b128 v[226:229], v204 offset:33024
	ds_read_b128 v[238:241], v220 offset:7168
	s_waitcnt lgkmcnt(3)
	v_mfma_f32_32x32x16_bf16 v[82:97], v[234:237], v[230:233], v[82:97]
	ds_read_b128 v[234:237], v204 offset:45312
	s_waitcnt lgkmcnt(3)
	v_mfma_f32_32x32x16_bf16 v[66:81], v[194:197], v[230:233], v[66:81]
	s_waitcnt lgkmcnt(1)
	v_mfma_f32_32x32x16_bf16 v[82:97], v[226:229], v[238:241], v[82:97]
	s_waitcnt lgkmcnt(0)
	v_mfma_f32_32x32x16_bf16 v[66:81], v[234:237], v[238:241], v[66:81]
	s_nop 1
	s_cbranch_scc1 .LBB0_736
	v_cmp_gt_i32_e64 s[70:71], 26, v221
	v_cmp_gt_i32_e64 s[72:73], 27, v221
	v_cmp_gt_i32_e64 s[68:69], 25, v221
	s_and_b64 s[70:71], s[72:73], s[70:71]
	v_cmp_gt_i32_e64 s[66:67], 24, v221
	s_and_b64 s[68:69], s[70:71], s[68:69]
	v_cmp_gt_i32_e64 s[64:65], 19, v221
	s_and_b64 s[66:67], s[68:69], s[66:67]
	v_cmp_gt_i32_e64 s[62:63], 18, v221
	s_and_b64 s[64:65], s[66:67], s[64:65]
	v_cmp_gt_i32_e64 s[56:57], 17, v221
	s_and_b64 s[62:63], s[64:65], s[62:63]
	v_cmp_gt_i32_e64 s[54:55], 16, v221
	s_and_b64 s[56:57], s[62:63], s[56:57]
	v_cmp_gt_i32_e64 s[52:53], 11, v221
	s_and_b64 s[54:55], s[56:57], s[54:55]
	v_cmp_gt_i32_e64 s[50:51], 10, v221
	s_and_b64 s[52:53], s[54:55], s[52:53]
	v_cmp_gt_i32_e64 s[48:49], 9, v221
	s_and_b64 s[50:51], s[52:53], s[50:51]
	v_cmp_gt_i32_e64 s[46:47], 8, v221
	s_and_b64 s[48:49], s[50:51], s[48:49]
	v_cmp_gt_i32_e64 s[44:45], 3, v221
	s_and_b64 s[46:47], s[48:49], s[46:47]
	v_cmp_gt_i32_e64 s[42:43], 2, v221
	s_and_b64 s[44:45], s[46:47], s[44:45]
	v_cmp_gt_i32_e64 s[40:41], 1, v221
	s_and_b64 s[42:43], s[44:45], s[42:43]
	v_cmp_gt_i32_e64 s[38:39], 0, v221
	s_and_b64 s[40:41], s[42:43], s[40:41]
	s_and_b64 s[38:39], s[40:41], s[38:39]
	v_cmp_gt_i32_e64 s[36:37], 58, v221
	v_cndmask_b32_e64 v82, v82, v216, s[38:39]
	v_cmp_gt_i32_e64 s[38:39], 59, v221
	v_cmp_gt_i32_e64 s[34:35], 57, v221
	s_and_b64 s[36:37], s[38:39], s[36:37]
	v_cmp_gt_i32_e64 s[0:1], 56, v221
	s_and_b64 s[34:35], s[36:37], s[34:35]
	v_cmp_gt_i32_e64 s[30:31], 51, v221
	s_and_b64 s[0:1], s[34:35], s[0:1]
	v_cmp_gt_i32_e64 s[28:29], 50, v221
	v_cndmask_b32_e64 v78, v78, v216, s[0:1]
	s_and_b64 s[0:1], s[0:1], s[30:31]
	v_cmp_gt_i32_e64 s[26:27], 49, v221
	v_cndmask_b32_e64 v77, v77, v216, s[0:1]
	s_and_b64 s[0:1], s[0:1], s[28:29]
	v_cmp_gt_i32_e64 s[24:25], 48, v221
	v_cndmask_b32_e64 v76, v76, v216, s[0:1]
	s_and_b64 s[0:1], s[0:1], s[26:27]
	v_cmp_gt_i32_e64 s[22:23], 43, v221
	v_cndmask_b32_e64 v75, v75, v216, s[0:1]
	s_and_b64 s[0:1], s[0:1], s[24:25]
	v_cmp_gt_i32_e64 s[20:21], 42, v221
	v_cndmask_b32_e64 v74, v74, v216, s[0:1]
	s_and_b64 s[0:1], s[0:1], s[22:23]
	v_cmp_gt_i32_e64 s[18:19], 41, v221
	v_cndmask_b32_e64 v73, v73, v216, s[0:1]
	s_and_b64 s[0:1], s[0:1], s[20:21]
	v_cmp_gt_i32_e64 s[16:17], 40, v221
	v_cndmask_b32_e64 v72, v72, v216, s[0:1]
	s_and_b64 s[0:1], s[0:1], s[18:19]
	v_cmp_gt_i32_e64 s[14:15], 35, v221
	v_cndmask_b32_e64 v71, v71, v216, s[0:1]
	s_and_b64 s[0:1], s[0:1], s[16:17]
	v_cmp_gt_i32_e64 s[12:13], 34, v221
	v_cndmask_b32_e64 v70, v70, v216, s[0:1]
	s_and_b64 s[0:1], s[0:1], s[14:15]
	v_cmp_gt_i32_e64 s[10:11], 33, v221
	v_cndmask_b32_e64 v69, v69, v216, s[0:1]
	s_and_b64 s[0:1], s[0:1], s[12:13]
	v_cmp_gt_i32_e32 vcc, 32, v221
	v_cndmask_b32_e64 v68, v68, v216, s[0:1]
	s_and_b64 s[0:1], s[0:1], s[10:11]
	s_and_b64 vcc, s[0:1], vcc
	v_cndmask_b32_e64 v97, v97, v216, s[72:73]
	v_cndmask_b32_e64 v96, v96, v216, s[70:71]
	v_cndmask_b32_e64 v95, v95, v216, s[68:69]
	v_cndmask_b32_e64 v94, v94, v216, s[66:67]
	v_cndmask_b32_e64 v93, v93, v216, s[64:65]
	v_cndmask_b32_e64 v92, v92, v216, s[62:63]
	v_cndmask_b32_e64 v91, v91, v216, s[56:57]
	v_cndmask_b32_e64 v90, v90, v216, s[54:55]
	v_cndmask_b32_e64 v89, v89, v216, s[52:53]
	v_cndmask_b32_e64 v88, v88, v216, s[50:51]
	v_cndmask_b32_e64 v87, v87, v216, s[48:49]
	v_cndmask_b32_e64 v86, v86, v216, s[46:47]
	v_cndmask_b32_e64 v85, v85, v216, s[44:45]
	v_cndmask_b32_e64 v84, v84, v216, s[42:43]
	v_cndmask_b32_e64 v83, v83, v216, s[40:41]
	v_cndmask_b32_e64 v81, v81, v216, s[38:39]
	v_cndmask_b32_e64 v80, v80, v216, s[36:37]
	v_cndmask_b32_e64 v79, v79, v216, s[34:35]
	v_cndmask_b32_e64 v67, v67, v216, s[0:1]
	v_cndmask_b32_e32 v66, v66, v216, vcc

.LBB0_742:
	s_cmp_lt_i32 s83, s77
	s_cselect_b64 s[94:95], -1, 0
	s_cmp_ge_i32 s83, s77
	s_cselect_b64 s[4:5], -1, 0
	s_and_b64 vcc, exec, s[4:5]
	s_waitcnt lgkmcnt(0)
	s_barrier
	s_cbranch_vccnz .LBB0_744
	v_add_u32_e32 v66, 0x80, v225
	v_ashrrev_i32_e32 v67, 31, v66
	v_add_u32_e32 v68, 0xa0, v225
	v_lshlrev_b64 v[66:67], 8, v[66:67]
	v_ashrrev_i32_e32 v69, 31, v68
	v_lshl_add_u64 v[66:67], v[192:193], 0, v[66:67]
	v_lshlrev_b64 v[68:69], 8, v[68:69]
	v_lshl_add_u64 v[68:69], v[192:193], 0, v[68:69]
	global_load_dwordx4 v[114:117], v[66:67], off
	global_load_dwordx4 v[118:121], v[68:69], off
	v_lshl_add_u64 v[66:67], s[78:79], 0, v[186:187]
	v_lshl_add_u64 v[68:69], s[78:79], 0, v[188:189]
	v_add_co_u32_e32 v66, vcc, 0x1700c000, v66
	s_nop 1
	v_addc_co_u32_e32 v67, vcc, 0, v67, vcc
	v_add_co_u32_e32 v68, vcc, 0x1700c000, v68
	s_nop 1
	v_addc_co_u32_e32 v69, vcc, 0, v69, vcc
	global_load_dwordx4 v[122:125], v[66:67], off
	global_load_dwordx4 v[126:129], v[68:69], off
	v_lshl_add_u64 v[66:67], s[78:79], 0, v[190:191]
	v_add_co_u32_e32 v66, vcc, 0x1700c000, v66
	s_nop 1
	v_addc_co_u32_e32 v67, vcc, 0, v67, vcc
	global_load_dwordx4 v[130:133], v[66:67], off
.LBB0_744:
	ds_read_b128 v[194:197], v139 offset:57344
	ds_read_b128 v[226:229], v205 offset:12288
	ds_read_b128 v[234:237], v202 offset:57344
	ds_read_b128 v[230:233], v220
	ds_read_b128 v[238:241], v220 offset:1024
	s_add_i32 s0, s84, 0x7f
	s_cmp_le_i32 s0, s82
	s_waitcnt lgkmcnt(4)
	v_mfma_f32_32x32x16_bf16 v[82:97], v[194:197], v[98:101], 0
	ds_read_b128 v[194:197], v206 offset:12288
	s_waitcnt lgkmcnt(4)
	v_mfma_f32_32x32x16_bf16 v[66:81], v[226:229], v[98:101], 0
	ds_read_b128 v[226:229], v203 offset:57344
	s_waitcnt lgkmcnt(4)
	v_mfma_f32_32x32x16_bf16 v[82:97], v[234:237], v[102:105], v[82:97]
	ds_read_b128 v[234:237], v207 offset:12288
	s_waitcnt lgkmcnt(2)
	v_mfma_f32_32x32x16_bf16 v[66:81], v[194:197], v[102:105], v[66:81]
	ds_read_b128 v[194:197], v204 offset:57344
	s_waitcnt lgkmcnt(2)
	v_mfma_f32_32x32x16_bf16 v[82:97], v[226:229], v[106:109], v[82:97]
	ds_read_b128 v[226:229], v208 offset:12288
	s_waitcnt lgkmcnt(2)
	v_mfma_f32_32x32x16_bf16 v[66:81], v[234:237], v[106:109], v[66:81]
	ds_read_b128 v[234:237], v139 offset:57472
	s_waitcnt lgkmcnt(2)
	v_mfma_f32_32x32x16_bf16 v[82:97], v[194:197], v[110:113], v[82:97]
	ds_read_b128 v[194:197], v205 offset:12416
	s_waitcnt lgkmcnt(2)
	v_mfma_f32_32x32x16_bf16 v[66:81], v[226:229], v[110:113], v[66:81]
	ds_read_b128 v[226:229], v202 offset:57472
	s_waitcnt lgkmcnt(2)
	v_mfma_f32_32x32x16_bf16 v[82:97], v[234:237], v[230:233], v[82:97]
	ds_read_b128 v[234:237], v206 offset:12416
	s_waitcnt lgkmcnt(2)
	v_mfma_f32_32x32x16_bf16 v[66:81], v[194:197], v[230:233], v[66:81]
	ds_read_b128 v[194:197], v203 offset:57472
	ds_read_b128 v[230:233], v220 offset:2048
	s_waitcnt lgkmcnt(3)
	v_mfma_f32_32x32x16_bf16 v[82:97], v[226:229], v[238:241], v[82:97]
	ds_read_b128 v[226:229], v207 offset:12416
	s_waitcnt lgkmcnt(3)
	v_mfma_f32_32x32x16_bf16 v[66:81], v[234:237], v[238:241], v[66:81]
	ds_read_b128 v[234:237], v204 offset:57472
	ds_read_b128 v[238:241], v220 offset:3072
	s_waitcnt lgkmcnt(3)
	v_mfma_f32_32x32x16_bf16 v[82:97], v[194:197], v[230:233], v[82:97]
	ds_read_b128 v[194:197], v208 offset:12416
	s_waitcnt lgkmcnt(3)
	v_mfma_f32_32x32x16_bf16 v[66:81], v[226:229], v[230:233], v[66:81]
	ds_read_b128 v[226:229], v139 offset:57600
	ds_read_b128 v[230:233], v220 offset:4096
	s_waitcnt lgkmcnt(3)
	v_mfma_f32_32x32x16_bf16 v[82:97], v[234:237], v[238:241], v[82:97]
	ds_read_b128 v[234:237], v205 offset:12544
	s_waitcnt lgkmcnt(3)
	v_mfma_f32_32x32x16_bf16 v[66:81], v[194:197], v[238:241], v[66:81]
	ds_read_b128 v[194:197], v202 offset:57600
	ds_read_b128 v[238:241], v220 offset:5120
	s_waitcnt lgkmcnt(3)
	v_mfma_f32_32x32x16_bf16 v[82:97], v[226:229], v[230:233], v[82:97]
	ds_read_b128 v[226:229], v206 offset:12544
	s_waitcnt lgkmcnt(3)
	v_mfma_f32_32x32x16_bf16 v[66:81], v[234:237], v[230:233], v[66:81]
	ds_read_b128 v[234:237], v203 offset:57600
	ds_read_b128 v[230:233], v220 offset:6144
	s_waitcnt lgkmcnt(3)
	v_mfma_f32_32x32x16_bf16 v[82:97], v[194:197], v[238:241], v[82:97]
	ds_read_b128 v[194:197], v207 offset:12544
	s_waitcnt lgkmcnt(3)
	v_mfma_f32_32x32x16_bf16 v[66:81], v[226:229], v[238:241], v[66:81]
	ds_read_b128 v[226:229], v204 offset:57600
	ds_read_b128 v[238:241], v220 offset:7168
	s_waitcnt lgkmcnt(3)
	v_mfma_f32_32x32x16_bf16 v[82:97], v[234:237], v[230:233], v[82:97]
	ds_read_b128 v[234:237], v208 offset:12544
	s_waitcnt lgkmcnt(3)
	v_mfma_f32_32x32x16_bf16 v[66:81], v[194:197], v[230:233], v[66:81]
	s_waitcnt lgkmcnt(1)
	v_mfma_f32_32x32x16_bf16 v[82:97], v[226:229], v[238:241], v[82:97]
	s_waitcnt lgkmcnt(0)
	v_mfma_f32_32x32x16_bf16 v[66:81], v[234:237], v[238:241], v[66:81]
	s_nop 1
	s_cbranch_scc1 .LBB0_746
	v_subrev_u32_e32 v194, 64, v221
	v_cmp_gt_i32_e64 s[70:71], 26, v194
	v_cmp_gt_i32_e64 s[72:73], 27, v194
	v_cmp_gt_i32_e64 s[68:69], 25, v194
	s_and_b64 s[70:71], s[72:73], s[70:71]
	v_cmp_gt_i32_e64 s[66:67], 24, v194
	s_and_b64 s[68:69], s[70:71], s[68:69]
	v_cmp_gt_i32_e64 s[64:65], 19, v194
	s_and_b64 s[66:67], s[68:69], s[66:67]
	v_cmp_gt_i32_e64 s[62:63], 18, v194
	s_and_b64 s[64:65], s[66:67], s[64:65]
	v_cmp_gt_i32_e64 s[56:57], 17, v194
	s_and_b64 s[62:63], s[64:65], s[62:63]
	v_cmp_gt_i32_e64 s[54:55], 16, v194
	s_and_b64 s[56:57], s[62:63], s[56:57]
	v_cmp_gt_i32_e64 s[52:53], 11, v194
	s_and_b64 s[54:55], s[56:57], s[54:55]
	v_cmp_gt_i32_e64 s[50:51], 10, v194
	s_and_b64 s[52:53], s[54:55], s[52:53]
	v_cmp_gt_i32_e64 s[48:49], 9, v194
	s_and_b64 s[50:51], s[52:53], s[50:51]
	v_cmp_gt_i32_e64 s[46:47], 8, v194
	s_and_b64 s[48:49], s[50:51], s[48:49]
	v_cmp_gt_i32_e64 s[44:45], 3, v194
	s_and_b64 s[46:47], s[48:49], s[46:47]
	v_cmp_gt_i32_e64 s[42:43], 2, v194
	s_and_b64 s[44:45], s[46:47], s[44:45]
	v_cmp_gt_i32_e64 s[40:41], 1, v194
	s_and_b64 s[42:43], s[44:45], s[42:43]
	v_cmp_gt_i32_e64 s[38:39], 0, v194
	s_and_b64 s[40:41], s[42:43], s[40:41]
	s_and_b64 s[38:39], s[40:41], s[38:39]
	v_cmp_gt_i32_e64 s[36:37], 58, v194
	v_cndmask_b32_e64 v82, v82, v216, s[38:39]
	v_cmp_gt_i32_e64 s[38:39], 59, v194
	v_cmp_gt_i32_e64 s[34:35], 57, v194
	s_and_b64 s[36:37], s[38:39], s[36:37]
	v_cmp_gt_i32_e64 s[0:1], 56, v194
	s_and_b64 s[34:35], s[36:37], s[34:35]
	v_cmp_gt_i32_e64 s[30:31], 51, v194
	s_and_b64 s[0:1], s[34:35], s[0:1]
	v_cmp_gt_i32_e64 s[28:29], 50, v194
	v_cndmask_b32_e64 v78, v78, v216, s[0:1]
	s_and_b64 s[0:1], s[0:1], s[30:31]
	v_cmp_gt_i32_e64 s[26:27], 49, v194
	v_cndmask_b32_e64 v77, v77, v216, s[0:1]
	s_and_b64 s[0:1], s[0:1], s[28:29]
	v_cmp_gt_i32_e64 s[24:25], 48, v194
	v_cndmask_b32_e64 v76, v76, v216, s[0:1]
	s_and_b64 s[0:1], s[0:1], s[26:27]
	v_cmp_gt_i32_e64 s[22:23], 43, v194
	v_cndmask_b32_e64 v75, v75, v216, s[0:1]
	s_and_b64 s[0:1], s[0:1], s[24:25]
	v_cmp_gt_i32_e64 s[20:21], 42, v194
	v_cndmask_b32_e64 v74, v74, v216, s[0:1]
	s_and_b64 s[0:1], s[0:1], s[22:23]
	v_cmp_gt_i32_e64 s[18:19], 41, v194
	v_cndmask_b32_e64 v73, v73, v216, s[0:1]
	s_and_b64 s[0:1], s[0:1], s[20:21]
	v_cmp_gt_i32_e64 s[16:17], 40, v194
	v_cndmask_b32_e64 v72, v72, v216, s[0:1]
	s_and_b64 s[0:1], s[0:1], s[18:19]
	v_cmp_gt_i32_e64 s[14:15], 35, v194
	v_cndmask_b32_e64 v71, v71, v216, s[0:1]
	s_and_b64 s[0:1], s[0:1], s[16:17]
	v_cmp_gt_i32_e64 s[12:13], 34, v194
	v_cndmask_b32_e64 v70, v70, v216, s[0:1]
	s_and_b64 s[0:1], s[0:1], s[14:15]
	v_cmp_gt_i32_e64 s[10:11], 33, v194
	v_cndmask_b32_e64 v69, v69, v216, s[0:1]
	s_and_b64 s[0:1], s[0:1], s[12:13]
	v_cmp_gt_i32_e32 vcc, 32, v194
	v_cndmask_b32_e64 v68, v68, v216, s[0:1]
	s_and_b64 s[0:1], s[0:1], s[10:11]
	s_and_b64 vcc, s[0:1], vcc
	v_cndmask_b32_e64 v97, v97, v216, s[72:73]
	v_cndmask_b32_e64 v96, v96, v216, s[70:71]
	v_cndmask_b32_e64 v95, v95, v216, s[68:69]
	v_cndmask_b32_e64 v94, v94, v216, s[66:67]
	v_cndmask_b32_e64 v93, v93, v216, s[64:65]
	v_cndmask_b32_e64 v92, v92, v216, s[62:63]
	v_cndmask_b32_e64 v91, v91, v216, s[56:57]
	v_cndmask_b32_e64 v90, v90, v216, s[54:55]
	v_cndmask_b32_e64 v89, v89, v216, s[52:53]
	v_cndmask_b32_e64 v88, v88, v216, s[50:51]
	v_cndmask_b32_e64 v87, v87, v216, s[48:49]
	v_cndmask_b32_e64 v86, v86, v216, s[46:47]
	v_cndmask_b32_e64 v85, v85, v216, s[44:45]
	v_cndmask_b32_e64 v84, v84, v216, s[42:43]
	v_cndmask_b32_e64 v83, v83, v216, s[40:41]
	v_cndmask_b32_e64 v81, v81, v216, s[38:39]
	v_cndmask_b32_e64 v80, v80, v216, s[36:37]
	v_cndmask_b32_e64 v79, v79, v216, s[34:35]
	v_cndmask_b32_e64 v67, v67, v216, s[0:1]
	v_cndmask_b32_e32 v66, v66, v216, vcc
